# cross-XCD work stealing disabled: each workgroup drains only its own XCD queue (removes serial probing of the 7 other queues at every phase end)
# speedup vs baseline: 1.0312x; 1.0312x over previous
;   __device__ __forceinline__ const float* x() const { return (const float*)(const __attribute__((address_space(1))) float*)kp[0]; }
; template <class F>
; __device__ __forceinline__ void xcd_schedule(int* q, int xcc, int ngroups, int gsize, char* smem, F f) {
;     ...
; #pragma unroll 1
;   for (int dy = 0; dy < 8; ++dy) {
;     const int y = (xcc + dy) & 7;
;     if (dy == 1) {
;       int t8 = threadIdx.x;
;       asm volatile("" : "+v"(t8));
;       if (t8 < 8) s_flag[t8] = __hip_atomic_load(&flags[t8], __ATOMIC_RELAXED, __HIP_MEMORY_SCOPE_AGENT);
;       __syncthreads();
;     }
;     if (dy >= 1 && __builtin_amdgcn_readfirstlane(s_flag[y]) != 0) continue;
;     for (;;) {
.LBB0_179:
	s_add_i32 s50, s50, 1
	s_add_i32 s49, s49, 1
	s_cmp_lg_u32 s50, 1
	s_cbranch_scc0 .LBB0_543

;   __device__ __forceinline__ const float* x() const { return (const float*)(const __attribute__((address_space(1))) float*)kp[0]; }
; template <class F>
; __device__ __forceinline__ void xcd_schedule(int* q, int xcc, int ngroups, int gsize, char* smem, F f) {
;     ...
; #pragma unroll 1
;   for (int dy = 0; dy < 8; ++dy) {
;     const int y = (xcc + dy) & 7;
;     if (dy == 1) {
;       int t8 = threadIdx.x;
;       asm volatile("" : "+v"(t8));
;       if (t8 < 8) s_flag[t8] = __hip_atomic_load(&flags[t8], __ATOMIC_RELAXED, __HIP_MEMORY_SCOPE_AGENT);
;       __syncthreads();
;     }
;     if (dy >= 1 && __builtin_amdgcn_readfirstlane(s_flag[y]) != 0) continue;
;     for (;;) {
.LBB0_594:
	s_add_i32 s16, s16, 1
	s_add_i32 s7, s7, 1
	s_add_i32 s6, s6, 1
	s_add_i32 s17, s17, 1
	s_cmp_lg_u32 s16, 1
	s_cbranch_scc0 .LBB0_1531

;   __device__ __forceinline__ const float* x() const { return (const float*)(const __attribute__((address_space(1))) float*)kp[0]; }
; template <class F>
; __device__ __forceinline__ void xcd_schedule(int* q, int xcc, int ngroups, int gsize, char* smem, F f) {
;     ...
; #pragma unroll 1
;   for (int dy = 0; dy < 8; ++dy) {
;     const int y = (xcc + dy) & 7;
;     if (dy == 1) {
;       int t8 = threadIdx.x;
;       asm volatile("" : "+v"(t8));
;       if (t8 < 8) s_flag[t8] = __hip_atomic_load(&flags[t8], __ATOMIC_RELAXED, __HIP_MEMORY_SCOPE_AGENT);
;       __syncthreads();
;     }
;     if (dy >= 1 && __builtin_amdgcn_readfirstlane(s_flag[y]) != 0) continue;
;     for (;;) {
.LBB0_1581:
	s_add_i32 s66, s66, 1
	s_add_i32 s89, s89, 1
	s_cmp_lg_u32 s66, 1
	s_cbranch_scc0 .LBB0_1672

;   __device__ __forceinline__ const float* x() const { return (const float*)(const __attribute__((address_space(1))) float*)kp[0]; }
; template <class F>
; __device__ __forceinline__ void xcd_schedule(int* q, int xcc, int ngroups, int gsize, char* smem, F f) {
;     ...
; #pragma unroll 1
;   for (int dy = 0; dy < 8; ++dy) {
;     const int y = (xcc + dy) & 7;
;     if (dy == 1) {
;       int t8 = threadIdx.x;
;       asm volatile("" : "+v"(t8));
;       if (t8 < 8) s_flag[t8] = __hip_atomic_load(&flags[t8], __ATOMIC_RELAXED, __HIP_MEMORY_SCOPE_AGENT);
;       __syncthreads();
;     }
;     if (dy >= 1 && __builtin_amdgcn_readfirstlane(s_flag[y]) != 0) continue;
;     for (;;) {
.LBB0_1722:
	s_add_i32 s8, s8, 1
	s_add_i32 s46, s46, 1
	s_cmp_lg_u32 s8, 1
	s_cbranch_scc0 .LBB0_1746

;   __device__ __forceinline__ const float* x() const { return (const float*)(const __attribute__((address_space(1))) float*)kp[0]; }
; template <class F>
; __device__ __forceinline__ void xcd_schedule(int* q, int xcc, int ngroups, int gsize, char* smem, F f) {
;     ...
; #pragma unroll 1
;   for (int dy = 0; dy < 8; ++dy) {
;     const int y = (xcc + dy) & 7;
;     if (dy == 1) {
;       int t8 = threadIdx.x;
;       asm volatile("" : "+v"(t8));
;       if (t8 < 8) s_flag[t8] = __hip_atomic_load(&flags[t8], __ATOMIC_RELAXED, __HIP_MEMORY_SCOPE_AGENT);
;       __syncthreads();
;     }
;     if (dy >= 1 && __builtin_amdgcn_readfirstlane(s_flag[y]) != 0) continue;
;     for (;;) {
.LBB0_1796:
	s_add_i32 s8, s8, 1
	s_add_i32 s48, s48, 1
	s_cmp_lg_u32 s8, 1
	s_cbranch_scc0 .LBB0_1818
